# P4,P6 16-row strips accumulated inside the 8-phase mainloop (4 extra MFMA per k-step per wave, A-strip via 12 KiB LDS ring), post-tile strip only epilogue
# speedup vs baseline: 1.0886x; 1.0250x over previous
; #define PG8_STAGE(bufoff, gbase, voff) do { _Pragma("unroll") for (int _i = 0; _i < 2; ++_i) \
;         __builtin_amdgcn_global_load_lds((const unsigned*)((const char*)(gbase) + (voff)[_i]), (LAS unsigned*)(lds + (bufoff) + ldsw + _i * 8192), 16, 0, 0); } while (0)
; #define PG8_LDA(dst, b, h) do { _Pragma("unroll") for (int m = 0; m < 4; ++m) _Pragma("unroll") for (int k = 0; k < 2; ++k) dst[m][k] = *(const LAS bf16x8*)(lds + PG8_SA(b, h) + aoff + m * 2048 + k * 1024); } while (0)
; #define PG8_LDB(dst, b, h) do { _Pragma("unroll") for (int n = 0; n < 2; ++n) _Pragma("unroll") for (int k = 0; k < 2; ++k) dst[n][k] = *(const LAS bf16x8*)(lds + PG8_SB(b, h) + boff + n * 2048 + k * 1024); } while (0)
; #define PG8_SCHED __builtin_amdgcn_sched_barrier(0)
; template <class Epi>
; __device__ __forceinline__ void gemm_phase(LAS unsigned char* lds, const Gemm g, const StaticOrder& S, const Epi& E) {
;     ...
;         const bool has_next = S.next(ui + 1, nxt);
;         const char* nA = has_next ? (const char*)g.A + (size_t)nxt.pm * tstep : cA; const char* nB = has_next ? (const char*)g.Bt + (size_t)nxt.pn * tstep : cB;
;         for (int t = 0; t < nt; t += 2) {
;             if constexpr (Epi::HAS_MID) { if (t == nt / 2) E.mid(acc, cur, wr, wc, fr, fq); }
;             const bool last = (t == nt - 2);
;             const char* a1 = cA + (size_t)(t + 1) * kstep;
;             const char* a2 = last ? nA : cA + (size_t)(t + 2) * kstep; const char* b2 = last ? nB : cB + (size_t)(t + 2) * kstep;
;             const char* a3 = a2 + kstep; const char* b3 = b2 + kstep;
;             PG8_LDB(B0, 0, 0); PG8_LDB(B1, 0, 1); PG8_SCHED; PG8_LDA(At, 0, 0); PG8_STAGE(PG8_SA(1, 1), a1 + hstep, voffA);
.LBB0_738:
	s_ashr_i32 s17, s16, 31
	s_lshl_b64 s[18:19], s[16:17], 19
	s_add_u32 s18, s33, s18
	s_addc_u32 s19, s34, s19
	s_and_b64 s[20:21], s[4:5], exec
	s_cselect_b32 s17, s19, s27
	s_cselect_b32 s23, s18, s26
	s_ashr_i32 s15, s14, 31
	s_lshl_b64 s[20:21], s[14:15], 19
	s_add_u32 s20, s35, s20
	s_addc_u32 s21, s36, s21
	s_and_b64 s[30:31], s[4:5], exec
	s_cselect_b32 s15, s21, s29
	s_cselect_b32 s25, s20, s28
	s_add_u32 s26, s26, 0x40080
	s_addc_u32 s27, s27, 0
	s_add_u32 s56, s28, 0x100
	v_mov_b32_e32 v0, 0
	s_addc_u32 s57, s29, 0
	s_mov_b32 s58, -2
	s_waitcnt lgkmcnt(0)
	v_readlane_b32 s70, v254, 21
	s_nop 3
	s_lshr_b32 s68, s70, 2
	s_cmp_lt_u32 s70, 4
	s_cselect_b32 s71, 1, 0
	s_lshl_b32 s72, s70, 10
	s_add_i32 s72, s72, 0x20000
	s_mov_b32 s69, 0
	s_mov_b64 s[74:75], 0x100
	s_and_b32 s76, s44, 7
	s_lshr_b32 s77, s44, 3
	s_and_b32 s77, s77, 7
	s_lshl_b32 s76, s76, 3
	s_add_i32 s76, s76, s77
	s_mulk_i32 s76, 0x110
	s_addk_i32 s76, 0x100
	s_mov_b32 s77, 0x800
	s_add_u32 s78, s88, 0x3000000
	s_addc_u32 s79, s89, 0
	s_lshl_b32 s73, s70, 6
	v_and_b32_e32 v250, 15, v132
	v_lshrrev_b32_e32 v251, 4, v132
	v_lshlrev_b32_e32 v251, 4, v251
	v_lshrrev_b32_e32 v252, 3, v250
	v_lshlrev_b32_e32 v252, 5, v252
	v_xor_b32_e32 v251, v251, v252
	v_lshl_add_u32 v246, v250, 6, v251
	v_add_u32_e32 v246, 0x20000, v246
	v_lshrrev_b32_e32 v250, 2, v132
	v_add_u32_e32 v250, s76, v250
	v_mul_lo_u32 v250, v250, s77
	v_and_b32_e32 v251, 3, v132
	v_lshlrev_b32_e32 v251, 4, v251
	v_lshrrev_b32_e32 v252, 5, v132
	v_lshlrev_b32_e32 v252, 5, v252
	v_xor_b32_e32 v251, v251, v252
	v_add3_u32 v248, v250, v251, s73
	v_mov_b32_e32 v249, 0
	v_lshl_add_u64 v[248:249], s[78:79], 0, v[248:249]
	v_mov_b32_e32 v230, 0
	v_mov_b32_e32 v231, 0
	v_mov_b32_e32 v232, 0
	v_mov_b32_e32 v233, 0
	v_mov_b32_e32 v234, 0
	v_mov_b32_e32 v235, 0
	v_mov_b32_e32 v236, 0
	v_mov_b32_e32 v237, 0
	s_cmp_eq_u32 s71, 0
	s_cbranch_scc1 .Lis_P4_i
	s_mov_b32 m0, s72
	s_nop 0
	global_load_lds_dwordx4 v[248:249], off
	v_lshl_add_u64 v[248:249], v[248:249], 0, s[74:75]
.Lis_P4_i:
	v_mov_b32_e32 v1, v0
	v_mov_b32_e32 v2, v0
	v_mov_b32_e32 v3, v0
	v_mov_b32_e32 v4, v0
	v_mov_b32_e32 v5, v0
	v_mov_b32_e32 v6, v0
	v_mov_b32_e32 v7, v0
	v_mov_b32_e32 v16, v0
	v_mov_b32_e32 v17, v0
	v_mov_b32_e32 v18, v0
	v_mov_b32_e32 v19, v0
	v_mov_b32_e32 v20, v0
	v_mov_b32_e32 v21, v0
	v_mov_b32_e32 v22, v0
	v_mov_b32_e32 v23, v0
	v_mov_b32_e32 v32, v0
	v_mov_b32_e32 v33, v0
	v_mov_b32_e32 v34, v0
	v_mov_b32_e32 v35, v0
	v_mov_b32_e32 v36, v0
	v_mov_b32_e32 v37, v0
	v_mov_b32_e32 v38, v0
	v_mov_b32_e32 v39, v0
	v_mov_b32_e32 v48, v0
	v_mov_b32_e32 v49, v0
	v_mov_b32_e32 v50, v0
	v_mov_b32_e32 v51, v0
	v_mov_b32_e32 v52, v0
	v_mov_b32_e32 v53, v0
	v_mov_b32_e32 v54, v0
	v_mov_b32_e32 v55, v0
	v_mov_b32_e32 v8, v0
	v_mov_b32_e32 v9, v0
	v_mov_b32_e32 v10, v0
	v_mov_b32_e32 v11, v0
	v_mov_b32_e32 v12, v0
	v_mov_b32_e32 v13, v0
	v_mov_b32_e32 v14, v0
	v_mov_b32_e32 v15, v0
	v_mov_b32_e32 v24, v0
	v_mov_b32_e32 v25, v0
	v_mov_b32_e32 v26, v0
	v_mov_b32_e32 v27, v0
	v_mov_b32_e32 v28, v0
	v_mov_b32_e32 v29, v0
	v_mov_b32_e32 v30, v0
	v_mov_b32_e32 v31, v0
	v_mov_b32_e32 v40, v0
	v_mov_b32_e32 v41, v0
	v_mov_b32_e32 v42, v0
	v_mov_b32_e32 v43, v0
	v_mov_b32_e32 v44, v0
	v_mov_b32_e32 v45, v0
	v_mov_b32_e32 v46, v0
	v_mov_b32_e32 v47, v0
	v_mov_b32_e32 v56, v0
	v_mov_b32_e32 v57, v0
	v_mov_b32_e32 v58, v0
	v_mov_b32_e32 v59, v0
	s_waitcnt vmcnt(0)
	v_mov_b32_e32 v60, v0
	v_mov_b32_e32 v61, v0
	v_mov_b32_e32 v62, v0
	v_mov_b32_e32 v63, v0
	v_mov_b32_e32 v64, v0
	v_mov_b32_e32 v65, v0
	v_mov_b32_e32 v66, v0
	v_mov_b32_e32 v67, v0
	v_mov_b32_e32 v68, v0
	v_mov_b32_e32 v69, v0
	v_mov_b32_e32 v70, v0
	v_mov_b32_e32 v71, v0
	v_mov_b32_e32 v80, v0
	v_mov_b32_e32 v81, v0
	v_mov_b32_e32 v82, v0
	v_mov_b32_e32 v83, v0
	v_mov_b32_e32 v84, v0
	v_mov_b32_e32 v85, v0
	v_mov_b32_e32 v86, v0
	v_mov_b32_e32 v87, v0
	v_mov_b32_e32 v96, v0
	v_mov_b32_e32 v97, v0
	v_mov_b32_e32 v98, v0
	v_mov_b32_e32 v99, v0
	v_mov_b32_e32 v100, v0
	v_mov_b32_e32 v101, v0
	v_mov_b32_e32 v102, v0
	v_mov_b32_e32 v103, v0
	v_mov_b32_e32 v112, v0
	v_mov_b32_e32 v113, v0
	v_mov_b32_e32 v114, v0
	v_mov_b32_e32 v115, v0
	v_mov_b32_e32 v116, v0
	v_mov_b32_e32 v117, v0
	v_mov_b32_e32 v118, v0
	v_mov_b32_e32 v119, v0
	v_mov_b32_e32 v72, v0
	v_mov_b32_e32 v73, v0
	v_mov_b32_e32 v74, v0
	v_mov_b32_e32 v75, v0
	v_mov_b32_e32 v76, v0
	v_mov_b32_e32 v77, v0
	v_mov_b32_e32 v78, v0
	v_mov_b32_e32 v79, v0
	v_mov_b32_e32 v88, v0
	v_mov_b32_e32 v89, v0
	v_mov_b32_e32 v90, v0
	v_mov_b32_e32 v91, v0
	v_mov_b32_e32 v92, v0
	v_mov_b32_e32 v93, v0
	v_mov_b32_e32 v94, v0
	v_mov_b32_e32 v95, v0
	v_mov_b32_e32 v104, v0
	v_mov_b32_e32 v105, v0
	v_mov_b32_e32 v106, v0
	v_mov_b32_e32 v107, v0
	v_mov_b32_e32 v108, v0
	v_mov_b32_e32 v109, v0
	v_mov_b32_e32 v110, v0
	v_mov_b32_e32 v111, v0
	v_mov_b32_e32 v120, v0
	v_mov_b32_e32 v121, v0
	v_mov_b32_e32 v122, v0
	v_mov_b32_e32 v123, v0
	v_mov_b32_e32 v124, v0
	v_mov_b32_e32 v125, v0
	v_mov_b32_e32 v126, v0
	v_mov_b32_e32 v127, v0
.LBB0_739:
	ds_read_b128 v[150:153], v157
	ds_read_b128 v[162:165], v157 offset:1024
	ds_read_b128 v[166:169], v157 offset:2048
	ds_read_b128 v[170:173], v157 offset:3072
	ds_read_b128 v[174:177], v158
	ds_read_b128 v[178:181], v158 offset:1024
	ds_read_b128 v[182:185], v158 offset:2048
	ds_read_b128 v[186:189], v158 offset:3072
	s_add_u32 s28, s26, 0xfffc0080
	s_addc_u32 s29, s27, -1
	s_cmp_eq_u32 s58, 12
	s_cselect_b32 s31, s17, s29
	s_cselect_b32 s30, s23, s28
	s_cselect_b32 s29, s15, s57
	s_cselect_b32 s28, s25, s56
	v_add_u32_e32 v247, s69, v246
	s_add_i32 s69, s69, 0x1000
	s_cmpk_eq_u32 s69, 0x3000
	s_cselect_b32 s69, 0, s69
	s_cmp_eq_u32 s71, 0
	s_cbranch_scc1 .Lis_P4_d
	s_add_i32 m0, s72, s69
	s_nop 0
	global_load_lds_dwordx4 v[248:249], off
	v_lshl_add_u64 v[248:249], v[248:249], 0, s[74:75]
; #define PG8_STAGE(bufoff, gbase, voff) do { _Pragma("unroll") for (int _i = 0; _i < 2; ++_i) \
;         __builtin_amdgcn_global_load_lds((const unsigned*)((const char*)(gbase) + (voff)[_i]), (LAS unsigned*)(lds + (bufoff) + ldsw + _i * 8192), 16, 0, 0); } while (0)
; #define PG8_LDA(dst, b, h) do { _Pragma("unroll") for (int m = 0; m < 4; ++m) _Pragma("unroll") for (int k = 0; k < 2; ++k) dst[m][k] = *(const LAS bf16x8*)(lds + PG8_SA(b, h) + aoff + m * 2048 + k * 1024); } while (0)
; #define PG8_LDB(dst, b, h) do { _Pragma("unroll") for (int n = 0; n < 2; ++n) _Pragma("unroll") for (int k = 0; k < 2; ++k) dst[n][k] = *(const LAS bf16x8*)(lds + PG8_SB(b, h) + boff + n * 2048 + k * 1024); } while (0)
; #define PG8_MMA(ai, bj, At, Bt) do { __builtin_amdgcn_s_setprio(1); _Pragma("unroll") for (int m = 0; m < 4; ++m) _Pragma("unroll") for (int n = 0; n < 2; ++n) _Pragma("unroll") for (int k = 0; k < 2; ++k) \
;         acc[ai][bj][m][n] = __builtin_amdgcn_mfma_f32_16x16x32_bf16(Bt[n][k], At[m][k], acc[ai][bj][m][n], 0, 0, 0); __builtin_amdgcn_s_setprio(0); } while (0)
; #define PG8_WAIT_V(n) asm volatile("s_waitcnt vmcnt(" #n ")" ::: "memory")
; #define PG8_WAIT_L(n) asm volatile("s_waitcnt lgkmcnt(" #n ")" ::: "memory")
; #define PG8_BAR __builtin_amdgcn_s_barrier()
; #define PG8_SCHED __builtin_amdgcn_sched_barrier(0)
; template <class Epi>
; __device__ __forceinline__ void gemm_phase(LAS unsigned char* lds, const Gemm g, const StaticOrder& S, const Epi& E) {
;     ...
;             PG8_LDB(B0, 0, 0); PG8_LDB(B1, 0, 1); PG8_SCHED; PG8_LDA(At, 0, 0); PG8_STAGE(PG8_SA(1, 1), a1 + hstep, voffA);
;             PG8_WAIT_V(8); PG8_WAIT_L(0); PG8_BAR; PG8_MMA(0, 0, At, B0); PG8_MMA(0, 1, At, B1); PG8_BAR; PG8_SCHED;
;             PG8_LDA(At, 0, 1); PG8_STAGE(PG8_SB(0, 0), b2, voffB); PG8_STAGE(PG8_SB(0, 1), b2 + hstep, voffB); PG8_STAGE(PG8_SA(0, 0), a2, voffA);
;             PG8_WAIT_V(8); PG8_WAIT_L(0); PG8_BAR; PG8_MMA(1, 0, At, B0); PG8_MMA(1, 1, At, B1); PG8_BAR; PG8_SCHED;
.Lis_P4_d:
	v_lshl_add_u64 v[154:155], s[26:27], 0, v[142:143]
	s_add_i32 m0, s38, 0xc000
	ds_read_b128 v[190:193], v159
	ds_read_b128 v[194:197], v159 offset:1024
	ds_read_b128 v[198:201], v159 offset:2048
	ds_read_b128 v[202:205], v159 offset:3072
	ds_read_b128 v[206:209], v159 offset:4096
	ds_read_b128 v[210:213], v159 offset:5120
	ds_read_b128 v[214:217], v159 offset:6144
	ds_read_b128 v[218:221], v159 offset:7168
	global_load_lds_dwordx4 v[154:155], off
	v_lshl_add_u64 v[154:155], s[26:27], 0, v[144:145]
	s_add_i32 m0, s38, 0xe000
	s_nop 0
	global_load_lds_dwordx4 v[154:155], off
	s_waitcnt vmcnt(8)
	s_waitcnt lgkmcnt(0)
	s_barrier
	s_setprio 1
	s_waitcnt lgkmcnt(0)
	v_mfma_f32_16x16x32_bf16 v[124:127], v[150:153], v[190:193], v[124:127]
	v_mfma_f32_16x16x32_bf16 v[120:123], v[166:169], v[190:193], v[120:123]
	v_mfma_f32_16x16x32_bf16 v[108:111], v[150:153], v[198:201], v[108:111]
	v_mfma_f32_16x16x32_bf16 v[104:107], v[166:169], v[198:201], v[104:107]
	v_mfma_f32_16x16x32_bf16 v[92:95], v[150:153], v[206:209], v[92:95]
	v_mfma_f32_16x16x32_bf16 v[88:91], v[166:169], v[206:209], v[88:91]
	v_mfma_f32_16x16x32_bf16 v[76:79], v[150:153], v[214:217], v[76:79]
	v_mfma_f32_16x16x32_bf16 v[72:75], v[166:169], v[214:217], v[72:75]
	v_mfma_f32_16x16x32_bf16 v[124:127], v[162:165], v[194:197], v[124:127]
	v_mfma_f32_16x16x32_bf16 v[120:123], v[170:173], v[194:197], v[120:123]
	v_mfma_f32_16x16x32_bf16 v[108:111], v[162:165], v[202:205], v[108:111]
	v_mfma_f32_16x16x32_bf16 v[104:107], v[170:173], v[202:205], v[104:107]
	v_mfma_f32_16x16x32_bf16 v[92:95], v[162:165], v[210:213], v[92:95]
	v_mfma_f32_16x16x32_bf16 v[88:91], v[170:173], v[210:213], v[88:91]
	v_mfma_f32_16x16x32_bf16 v[76:79], v[162:165], v[218:221], v[76:79]
	v_mfma_f32_16x16x32_bf16 v[72:75], v[170:173], v[218:221], v[72:75]
	s_setprio 0
	s_setprio 1
	v_mfma_f32_16x16x32_bf16 v[116:119], v[174:177], v[190:193], v[116:119]
	v_mfma_f32_16x16x32_bf16 v[112:115], v[182:185], v[190:193], v[112:115]
	v_mfma_f32_16x16x32_bf16 v[100:103], v[174:177], v[198:201], v[100:103]
	v_mfma_f32_16x16x32_bf16 v[96:99], v[182:185], v[198:201], v[96:99]
	v_mfma_f32_16x16x32_bf16 v[84:87], v[174:177], v[206:209], v[84:87]
	v_mfma_f32_16x16x32_bf16 v[80:83], v[182:185], v[206:209], v[80:83]
	v_mfma_f32_16x16x32_bf16 v[68:71], v[174:177], v[214:217], v[68:71]
	v_mfma_f32_16x16x32_bf16 v[64:67], v[182:185], v[214:217], v[64:67]
	v_mfma_f32_16x16x32_bf16 v[116:119], v[178:181], v[194:197], v[116:119]
	v_mfma_f32_16x16x32_bf16 v[112:115], v[186:189], v[194:197], v[112:115]
	v_mfma_f32_16x16x32_bf16 v[100:103], v[178:181], v[202:205], v[100:103]
	v_mfma_f32_16x16x32_bf16 v[96:99], v[186:189], v[202:205], v[96:99]
	v_mfma_f32_16x16x32_bf16 v[84:87], v[178:181], v[210:213], v[84:87]
	v_mfma_f32_16x16x32_bf16 v[80:83], v[186:189], v[210:213], v[80:83]
	v_mfma_f32_16x16x32_bf16 v[68:71], v[178:181], v[218:221], v[68:71]
	v_mfma_f32_16x16x32_bf16 v[64:67], v[186:189], v[218:221], v[64:67]
	s_setprio 0
	s_barrier
	s_add_i32 s59, s49, s37
	v_lshl_add_u64 v[154:155], s[28:29], 0, v[130:131]
	s_mov_b32 m0, s59
	ds_read_b128 v[190:193], v159 offset:16384
	ds_read_b128 v[194:197], v159 offset:17408
	ds_read_b128 v[198:201], v159 offset:18432
	ds_read_b128 v[202:205], v159 offset:19456
	ds_read_b128 v[206:209], v159 offset:20480
	ds_read_b128 v[210:213], v159 offset:21504
	ds_read_b128 v[214:217], v159 offset:22528
	ds_read_b128 v[218:221], v159 offset:23552
	ds_read_b128 v[238:241], v247
	ds_read_b128 v[242:245], v247 offset:1024
	global_load_lds_dwordx4 v[154:155], off
	s_add_i32 m0, s59, 0x2000
	s_add_u32 s60, s28, 0x40000
	v_lshl_add_u64 v[222:223], s[28:29], 0, v[138:139]
	s_addc_u32 s61, s29, 0
	s_add_i32 s59, s50, s37
	global_load_lds_dwordx4 v[222:223], off
	v_lshl_add_u64 v[224:225], s[60:61], 0, v[130:131]
	s_mov_b32 m0, s59
	v_lshl_add_u64 v[226:227], s[30:31], 0, v[136:137]
	global_load_lds_dwordx4 v[224:225], off
	v_lshl_add_u64 v[224:225], s[60:61], 0, v[138:139]
	s_add_i32 m0, s59, 0x2000
	s_nop 0
	global_load_lds_dwordx4 v[224:225], off
	v_lshl_add_u64 v[224:225], s[30:31], 0, v[128:129]
	s_mov_b32 m0, s38
	s_nop 0
	global_load_lds_dwordx4 v[224:225], off
	s_mov_b32 m0, s39
	s_nop 0
	global_load_lds_dwordx4 v[226:227], off
	s_waitcnt vmcnt(8)
	s_waitcnt lgkmcnt(0)
	s_barrier
	s_setprio 1
	s_waitcnt lgkmcnt(0)
	v_mfma_f32_16x16x32_bf16 v[60:63], v[150:153], v[190:193], v[60:63]
	v_mfma_f32_16x16x32_bf16 v[56:59], v[166:169], v[190:193], v[56:59]
	v_mfma_f32_16x16x32_bf16 v[44:47], v[150:153], v[198:201], v[44:47]
	v_mfma_f32_16x16x32_bf16 v[40:43], v[166:169], v[198:201], v[40:43]
	v_mfma_f32_16x16x32_bf16 v[28:31], v[150:153], v[206:209], v[28:31]
	v_mfma_f32_16x16x32_bf16 v[24:27], v[166:169], v[206:209], v[24:27]
	v_mfma_f32_16x16x32_bf16 v[12:15], v[150:153], v[214:217], v[12:15]
	v_mfma_f32_16x16x32_bf16 v[8:11], v[166:169], v[214:217], v[8:11]
	v_mfma_f32_16x16x32_bf16 v[60:63], v[162:165], v[194:197], v[60:63]
	v_mfma_f32_16x16x32_bf16 v[56:59], v[170:173], v[194:197], v[56:59]
	v_mfma_f32_16x16x32_bf16 v[44:47], v[162:165], v[202:205], v[44:47]
	v_mfma_f32_16x16x32_bf16 v[40:43], v[170:173], v[202:205], v[40:43]
	v_mfma_f32_16x16x32_bf16 v[28:31], v[162:165], v[210:213], v[28:31]
	v_mfma_f32_16x16x32_bf16 v[24:27], v[170:173], v[210:213], v[24:27]
	v_mfma_f32_16x16x32_bf16 v[12:15], v[162:165], v[218:221], v[12:15]
	v_mfma_f32_16x16x32_bf16 v[8:11], v[170:173], v[218:221], v[8:11]
	s_setprio 0
	s_setprio 1
	v_mfma_f32_16x16x32_bf16 v[52:55], v[174:177], v[190:193], v[52:55]
	v_mfma_f32_16x16x32_bf16 v[48:51], v[182:185], v[190:193], v[48:51]
	v_mfma_f32_16x16x32_bf16 v[36:39], v[174:177], v[198:201], v[36:39]
	v_mfma_f32_16x16x32_bf16 v[32:35], v[182:185], v[198:201], v[32:35]
	v_mfma_f32_16x16x32_bf16 v[20:23], v[174:177], v[206:209], v[20:23]
	v_mfma_f32_16x16x32_bf16 v[16:19], v[182:185], v[206:209], v[16:19]
	v_mfma_f32_16x16x32_bf16 v[4:7], v[174:177], v[214:217], v[4:7]
	v_mfma_f32_16x16x32_bf16 v[0:3], v[182:185], v[214:217], v[0:3]
	v_mfma_f32_16x16x32_bf16 v[52:55], v[178:181], v[194:197], v[52:55]
	v_mfma_f32_16x16x32_bf16 v[48:51], v[186:189], v[194:197], v[48:51]
	v_mfma_f32_16x16x32_bf16 v[36:39], v[178:181], v[202:205], v[36:39]
	v_mfma_f32_16x16x32_bf16 v[32:35], v[186:189], v[202:205], v[32:35]
	v_mfma_f32_16x16x32_bf16 v[20:23], v[178:181], v[210:213], v[20:23]
	v_mfma_f32_16x16x32_bf16 v[16:19], v[186:189], v[210:213], v[16:19]
	v_mfma_f32_16x16x32_bf16 v[4:7], v[178:181], v[218:221], v[4:7]
	v_mfma_f32_16x16x32_bf16 v[0:3], v[186:189], v[218:221], v[0:3]
	s_cmp_eq_u32 s68, 0
	s_cbranch_scc1 .Lis_P4_b0
	v_mfma_f32_16x16x32_bf16 v[230:233], v[174:177], v[238:241], v[230:233]
	v_mfma_f32_16x16x32_bf16 v[234:237], v[182:185], v[238:241], v[234:237]
	v_mfma_f32_16x16x32_bf16 v[230:233], v[178:181], v[242:245], v[230:233]
	v_mfma_f32_16x16x32_bf16 v[234:237], v[186:189], v[242:245], v[234:237]
	s_branch .Lis_P4_bj
; #define PG8_STAGE(bufoff, gbase, voff) do { _Pragma("unroll") for (int _i = 0; _i < 2; ++_i) \
;         __builtin_amdgcn_global_load_lds((const unsigned*)((const char*)(gbase) + (voff)[_i]), (LAS unsigned*)(lds + (bufoff) + ldsw + _i * 8192), 16, 0, 0); } while (0)
; #define PG8_LDA(dst, b, h) do { _Pragma("unroll") for (int m = 0; m < 4; ++m) _Pragma("unroll") for (int k = 0; k < 2; ++k) dst[m][k] = *(const LAS bf16x8*)(lds + PG8_SA(b, h) + aoff + m * 2048 + k * 1024); } while (0)
; #define PG8_LDB(dst, b, h) do { _Pragma("unroll") for (int n = 0; n < 2; ++n) _Pragma("unroll") for (int k = 0; k < 2; ++k) dst[n][k] = *(const LAS bf16x8*)(lds + PG8_SB(b, h) + boff + n * 2048 + k * 1024); } while (0)
; #define PG8_MMA(ai, bj, At, Bt) do { __builtin_amdgcn_s_setprio(1); _Pragma("unroll") for (int m = 0; m < 4; ++m) _Pragma("unroll") for (int n = 0; n < 2; ++n) _Pragma("unroll") for (int k = 0; k < 2; ++k) \
;         acc[ai][bj][m][n] = __builtin_amdgcn_mfma_f32_16x16x32_bf16(Bt[n][k], At[m][k], acc[ai][bj][m][n], 0, 0, 0); __builtin_amdgcn_s_setprio(0); } while (0)
; #define PG8_WAIT_V(n) asm volatile("s_waitcnt vmcnt(" #n ")" ::: "memory")
; #define PG8_WAIT_L(n) asm volatile("s_waitcnt lgkmcnt(" #n ")" ::: "memory")
; #define PG8_BAR __builtin_amdgcn_s_barrier()
; #define PG8_SCHED __builtin_amdgcn_sched_barrier(0)
; template <class Epi>
; __device__ __forceinline__ void gemm_phase(LAS unsigned char* lds, const Gemm g, const StaticOrder& S, const Epi& E) {
;     ...
;             PG8_WAIT_V(8); PG8_WAIT_L(0); PG8_BAR; PG8_MMA(1, 0, At, B0); PG8_MMA(1, 1, At, B1); PG8_BAR; PG8_SCHED;
;             PG8_LDB(B0, 1, 0); PG8_LDB(B1, 1, 1); PG8_SCHED; PG8_LDA(At, 1, 0); PG8_STAGE(PG8_SA(0, 1), a2 + hstep, voffA);
;             PG8_WAIT_V(8); PG8_WAIT_L(0); PG8_BAR; PG8_MMA(0, 0, At, B0); PG8_MMA(0, 1, At, B1); PG8_BAR; PG8_SCHED;
.Lis_P4_b0:
	v_mfma_f32_16x16x32_bf16 v[230:233], v[150:153], v[238:241], v[230:233]
	v_mfma_f32_16x16x32_bf16 v[234:237], v[166:169], v[238:241], v[234:237]
	v_mfma_f32_16x16x32_bf16 v[230:233], v[162:165], v[242:245], v[230:233]
	v_mfma_f32_16x16x32_bf16 v[234:237], v[170:173], v[242:245], v[234:237]
.Lis_P4_bj:
	s_setprio 0
	s_barrier
	s_add_i32 s59, 0, 0x18000
	v_add_u32_e32 v140, s59, v135
	s_add_i32 s60, 0, 0x1c000
	ds_read_b128 v[150:153], v140
	ds_read_b128 v[162:165], v140 offset:1024
	ds_read_b128 v[166:169], v140 offset:2048
	ds_read_b128 v[170:173], v140 offset:3072
	v_add_u32_e32 v140, s60, v135
	ds_read_b128 v[174:177], v140
	ds_read_b128 v[178:181], v140 offset:1024
	ds_read_b128 v[182:185], v140 offset:2048
	ds_read_b128 v[186:189], v140 offset:3072
	s_add_u32 s30, s30, 0x40000
	s_addc_u32 s31, s31, 0
	s_mov_b32 m0, s40
	v_lshl_add_u64 v[228:229], s[30:31], 0, v[128:129]
	ds_read_b128 v[190:193], v159 offset:32768
	ds_read_b128 v[194:197], v159 offset:33792
	ds_read_b128 v[198:201], v159 offset:34816
	ds_read_b128 v[202:205], v159 offset:35840
	ds_read_b128 v[206:209], v159 offset:36864
	ds_read_b128 v[210:213], v159 offset:37888
	ds_read_b128 v[214:217], v159 offset:38912
	ds_read_b128 v[218:221], v159 offset:39936
	global_load_lds_dwordx4 v[228:229], off
	v_lshl_add_u64 v[228:229], s[30:31], 0, v[136:137]
	s_mov_b32 m0, s41
	s_nop 0
	global_load_lds_dwordx4 v[228:229], off
	s_waitcnt vmcnt(8)
	s_waitcnt lgkmcnt(0)
	s_barrier
	s_setprio 1
	s_waitcnt lgkmcnt(0)
	v_mfma_f32_16x16x32_bf16 v[124:127], v[150:153], v[190:193], v[124:127]
	v_mfma_f32_16x16x32_bf16 v[120:123], v[166:169], v[190:193], v[120:123]
	v_mfma_f32_16x16x32_bf16 v[108:111], v[150:153], v[198:201], v[108:111]
	v_mfma_f32_16x16x32_bf16 v[104:107], v[166:169], v[198:201], v[104:107]
	v_mfma_f32_16x16x32_bf16 v[92:95], v[150:153], v[206:209], v[92:95]
	v_mfma_f32_16x16x32_bf16 v[88:91], v[166:169], v[206:209], v[88:91]
	v_mfma_f32_16x16x32_bf16 v[76:79], v[150:153], v[214:217], v[76:79]
	v_mfma_f32_16x16x32_bf16 v[72:75], v[166:169], v[214:217], v[72:75]
	v_mfma_f32_16x16x32_bf16 v[124:127], v[162:165], v[194:197], v[124:127]
	v_mfma_f32_16x16x32_bf16 v[120:123], v[170:173], v[194:197], v[120:123]
	v_mfma_f32_16x16x32_bf16 v[108:111], v[162:165], v[202:205], v[108:111]
	v_mfma_f32_16x16x32_bf16 v[104:107], v[170:173], v[202:205], v[104:107]
	v_mfma_f32_16x16x32_bf16 v[92:95], v[162:165], v[210:213], v[92:95]
	v_mfma_f32_16x16x32_bf16 v[88:91], v[170:173], v[210:213], v[88:91]
	v_mfma_f32_16x16x32_bf16 v[76:79], v[162:165], v[218:221], v[76:79]
	v_mfma_f32_16x16x32_bf16 v[72:75], v[170:173], v[218:221], v[72:75]
	s_setprio 0
	s_setprio 1
	v_mfma_f32_16x16x32_bf16 v[116:119], v[174:177], v[190:193], v[116:119]
	v_mfma_f32_16x16x32_bf16 v[112:115], v[182:185], v[190:193], v[112:115]
	v_mfma_f32_16x16x32_bf16 v[100:103], v[174:177], v[198:201], v[100:103]
	v_mfma_f32_16x16x32_bf16 v[96:99], v[182:185], v[198:201], v[96:99]
	v_mfma_f32_16x16x32_bf16 v[84:87], v[174:177], v[206:209], v[84:87]
	v_mfma_f32_16x16x32_bf16 v[80:83], v[182:185], v[206:209], v[80:83]
	v_mfma_f32_16x16x32_bf16 v[68:71], v[174:177], v[214:217], v[68:71]
	v_mfma_f32_16x16x32_bf16 v[64:67], v[182:185], v[214:217], v[64:67]
	v_mfma_f32_16x16x32_bf16 v[116:119], v[178:181], v[194:197], v[116:119]
	v_mfma_f32_16x16x32_bf16 v[112:115], v[186:189], v[194:197], v[112:115]
	v_mfma_f32_16x16x32_bf16 v[100:103], v[178:181], v[202:205], v[100:103]
	v_mfma_f32_16x16x32_bf16 v[96:99], v[186:189], v[202:205], v[96:99]
	v_mfma_f32_16x16x32_bf16 v[84:87], v[178:181], v[210:213], v[84:87]
	v_mfma_f32_16x16x32_bf16 v[80:83], v[186:189], v[210:213], v[80:83]
	v_mfma_f32_16x16x32_bf16 v[68:71], v[178:181], v[218:221], v[68:71]
	v_mfma_f32_16x16x32_bf16 v[64:67], v[186:189], v[218:221], v[64:67]
	s_setprio 0
	s_barrier
; #define PG8_STAGE(bufoff, gbase, voff) do { _Pragma("unroll") for (int _i = 0; _i < 2; ++_i) \
;         __builtin_amdgcn_global_load_lds((const unsigned*)((const char*)(gbase) + (voff)[_i]), (LAS unsigned*)(lds + (bufoff) + ldsw + _i * 8192), 16, 0, 0); } while (0)
; #define PG8_LDA(dst, b, h) do { _Pragma("unroll") for (int m = 0; m < 4; ++m) _Pragma("unroll") for (int k = 0; k < 2; ++k) dst[m][k] = *(const LAS bf16x8*)(lds + PG8_SA(b, h) + aoff + m * 2048 + k * 1024); } while (0)
; #define PG8_MMA(ai, bj, At, Bt) do { __builtin_amdgcn_s_setprio(1); _Pragma("unroll") for (int m = 0; m < 4; ++m) _Pragma("unroll") for (int n = 0; n < 2; ++n) _Pragma("unroll") for (int k = 0; k < 2; ++k) \
;         acc[ai][bj][m][n] = __builtin_amdgcn_mfma_f32_16x16x32_bf16(Bt[n][k], At[m][k], acc[ai][bj][m][n], 0, 0, 0); __builtin_amdgcn_s_setprio(0); } while (0)
; #define PG8_WAIT_V(n) asm volatile("s_waitcnt vmcnt(" #n ")" ::: "memory")
; #define PG8_WAIT_L(n) asm volatile("s_waitcnt lgkmcnt(" #n ")" ::: "memory")
; #define PG8_BAR __builtin_amdgcn_s_barrier()
; #define PG8_SCHED __builtin_amdgcn_sched_barrier(0)
; template <class Epi>
; __device__ __forceinline__ void gemm_phase(LAS unsigned char* lds, const Gemm g, const StaticOrder& S, const Epi& E) {
;     ...
;             PG8_WAIT_V(8); PG8_WAIT_L(0); PG8_BAR; PG8_MMA(0, 0, At, B0); PG8_MMA(0, 1, At, B1); PG8_BAR; PG8_SCHED;
;             PG8_LDA(At, 1, 1); PG8_STAGE(PG8_SB(1, 0), b3, voffB); PG8_STAGE(PG8_SB(1, 1), b3 + hstep, voffB); PG8_STAGE(PG8_SA(1, 0), a3, voffA);
;             PG8_WAIT_V(8); PG8_WAIT_L(0); PG8_BAR; PG8_MMA(1, 0, At, B0); PG8_MMA(1, 1, At, B1); PG8_BAR; PG8_SCHED;
	s_add_i32 s30, s59, s37
	v_lshl_add_u64 v[154:155], v[154:155], 0, s[10:11]
	s_mov_b32 m0, s30
	ds_read_b128 v[190:193], v159 offset:49152
	ds_read_b128 v[194:197], v159 offset:50176
	ds_read_b128 v[198:201], v159 offset:51200
	ds_read_b128 v[202:205], v159 offset:52224
	ds_read_b128 v[206:209], v159 offset:53248
	ds_read_b128 v[210:213], v159 offset:54272
	ds_read_b128 v[214:217], v159 offset:55296
	ds_read_b128 v[218:221], v159 offset:56320
	ds_read_b128 v[238:241], v247 offset:2048
	ds_read_b128 v[242:245], v247 offset:3072
	global_load_lds_dwordx4 v[154:155], off
	s_add_i32 m0, s30, 0x2000
	s_add_u32 s28, s28, 0x40080
	v_lshl_add_u64 v[154:155], v[222:223], 0, s[10:11]
	s_addc_u32 s29, s29, 0
	s_add_i32 s30, s60, s37
	global_load_lds_dwordx4 v[154:155], off
	v_lshl_add_u64 v[154:155], s[28:29], 0, v[130:131]
	s_mov_b32 m0, s30
	s_nop 0
	global_load_lds_dwordx4 v[154:155], off
	v_lshl_add_u64 v[154:155], s[28:29], 0, v[138:139]
	s_add_i32 m0, s30, 0x2000
	s_nop 0
	global_load_lds_dwordx4 v[154:155], off
	v_lshl_add_u64 v[154:155], v[224:225], 0, s[10:11]
	s_mov_b32 m0, s43
	s_nop 0
	global_load_lds_dwordx4 v[154:155], off
	v_lshl_add_u64 v[154:155], v[226:227], 0, s[10:11]
	s_mov_b32 m0, s45
	s_nop 0
	global_load_lds_dwordx4 v[154:155], off
	s_waitcnt vmcnt(8)
	s_waitcnt lgkmcnt(0)
	s_barrier
	s_setprio 1
	s_waitcnt lgkmcnt(0)
	v_mfma_f32_16x16x32_bf16 v[60:63], v[150:153], v[190:193], v[60:63]
	v_mfma_f32_16x16x32_bf16 v[56:59], v[166:169], v[190:193], v[56:59]
	v_mfma_f32_16x16x32_bf16 v[44:47], v[150:153], v[198:201], v[44:47]
	v_mfma_f32_16x16x32_bf16 v[40:43], v[166:169], v[198:201], v[40:43]
	v_mfma_f32_16x16x32_bf16 v[28:31], v[150:153], v[206:209], v[28:31]
	v_mfma_f32_16x16x32_bf16 v[24:27], v[166:169], v[206:209], v[24:27]
	v_mfma_f32_16x16x32_bf16 v[12:15], v[150:153], v[214:217], v[12:15]
	v_mfma_f32_16x16x32_bf16 v[8:11], v[166:169], v[214:217], v[8:11]
	v_mfma_f32_16x16x32_bf16 v[60:63], v[162:165], v[194:197], v[60:63]
	v_mfma_f32_16x16x32_bf16 v[56:59], v[170:173], v[194:197], v[56:59]
	v_mfma_f32_16x16x32_bf16 v[44:47], v[162:165], v[202:205], v[44:47]
	v_mfma_f32_16x16x32_bf16 v[40:43], v[170:173], v[202:205], v[40:43]
	v_mfma_f32_16x16x32_bf16 v[28:31], v[162:165], v[210:213], v[28:31]
	v_mfma_f32_16x16x32_bf16 v[24:27], v[170:173], v[210:213], v[24:27]
	v_mfma_f32_16x16x32_bf16 v[12:15], v[162:165], v[218:221], v[12:15]
	v_mfma_f32_16x16x32_bf16 v[8:11], v[170:173], v[218:221], v[8:11]
	s_setprio 0
	s_setprio 1
	v_mfma_f32_16x16x32_bf16 v[52:55], v[174:177], v[190:193], v[52:55]
	v_mfma_f32_16x16x32_bf16 v[48:51], v[182:185], v[190:193], v[48:51]
	v_mfma_f32_16x16x32_bf16 v[36:39], v[174:177], v[198:201], v[36:39]
	v_mfma_f32_16x16x32_bf16 v[32:35], v[182:185], v[198:201], v[32:35]
	v_mfma_f32_16x16x32_bf16 v[20:23], v[174:177], v[206:209], v[20:23]
	v_mfma_f32_16x16x32_bf16 v[16:19], v[182:185], v[206:209], v[16:19]
	v_mfma_f32_16x16x32_bf16 v[4:7], v[174:177], v[214:217], v[4:7]
	v_mfma_f32_16x16x32_bf16 v[0:3], v[182:185], v[214:217], v[0:3]
	v_mfma_f32_16x16x32_bf16 v[52:55], v[178:181], v[194:197], v[52:55]
	v_mfma_f32_16x16x32_bf16 v[48:51], v[186:189], v[194:197], v[48:51]
	v_mfma_f32_16x16x32_bf16 v[36:39], v[178:181], v[202:205], v[36:39]
	v_mfma_f32_16x16x32_bf16 v[32:35], v[186:189], v[202:205], v[32:35]
	v_mfma_f32_16x16x32_bf16 v[20:23], v[178:181], v[210:213], v[20:23]
	v_mfma_f32_16x16x32_bf16 v[16:19], v[186:189], v[210:213], v[16:19]
	v_mfma_f32_16x16x32_bf16 v[4:7], v[178:181], v[218:221], v[4:7]
	v_mfma_f32_16x16x32_bf16 v[0:3], v[186:189], v[218:221], v[0:3]
	s_cmp_eq_u32 s68, 0
	s_cbranch_scc1 .Lis_P4_d0
	v_mfma_f32_16x16x32_bf16 v[230:233], v[174:177], v[238:241], v[230:233]
	v_mfma_f32_16x16x32_bf16 v[234:237], v[182:185], v[238:241], v[234:237]
	v_mfma_f32_16x16x32_bf16 v[230:233], v[178:181], v[242:245], v[230:233]
	v_mfma_f32_16x16x32_bf16 v[234:237], v[186:189], v[242:245], v[234:237]
	s_branch .Lis_P4_dj

; #define PG8_MMA(ai, bj, At, Bt) do { __builtin_amdgcn_s_setprio(1); _Pragma("unroll") for (int m = 0; m < 4; ++m) _Pragma("unroll") for (int n = 0; n < 2; ++n) _Pragma("unroll") for (int k = 0; k < 2; ++k) \
;         acc[ai][bj][m][n] = __builtin_amdgcn_mfma_f32_16x16x32_bf16(Bt[n][k], At[m][k], acc[ai][bj][m][n], 0, 0, 0); __builtin_amdgcn_s_setprio(0); } while (0)
; #define PG8_WAIT_V(n) asm volatile("s_waitcnt vmcnt(" #n ")" ::: "memory")
; #define PG8_WAIT_L(n) asm volatile("s_waitcnt lgkmcnt(" #n ")" ::: "memory")
; #define PG8_BAR __builtin_amdgcn_s_barrier()
; #define PG8_SCHED __builtin_amdgcn_sched_barrier(0)
; template <class Epi>
; __device__ __forceinline__ void gemm_phase(LAS unsigned char* lds, const Gemm g, const StaticOrder& S, const Epi& E) {
;     ...
;             PG8_WAIT_V(8); PG8_WAIT_L(0); PG8_BAR; PG8_MMA(1, 0, At, B0); PG8_MMA(1, 1, At, B1); PG8_BAR; PG8_SCHED;
;         }
;         if (wr == 0) PG8_BAR;
.Lis_P4_dj:
	s_setprio 0
	s_barrier
	s_add_i32 s58, s58, 2
	s_add_u32 s26, s26, 0x100
	s_addc_u32 s27, s27, 0
	s_add_u32 s56, s56, 0x100
	s_addc_u32 s57, s57, 0
	s_cmp_gt_u32 s58, 13
	s_cbranch_scc0 .LBB0_739
	s_and_b64 vcc, exec, s[12:13]
	s_cbranch_vccz .LBB0_742
	s_barrier

; __device__ __forceinline__ u32x4 pack8(f32x4 a, f32x4 b) { u32x4 w; w.x = cvt_pk_bf16(a[0], a[1]); w.y = cvt_pk_bf16(a[2], a[3]); w.z = cvt_pk_bf16(b[0], b[1]); w.w = cvt_pk_bf16(b[2], b[3]); return w; }
;     __device__ __forceinline__ void operator()(const f32x4 (&acc)[2][2][4][2], const pg8::Unit& u, int wr, int wc, int fr, int fq) const {
;     ...
;             for (int m = 0; m < 4; ++m) { const int row = u.pm * 256 + ai * 128 + wr * 64 + m * 16 + fr; float ss = 0.f;
;                 const float* xrow = row < MP ? xp + (size_t)row * D : xs + (size_t)(row - MP) * D;
; #pragma unroll
;                 for (int bj = 0; bj < 2; ++bj) { const int col = u.pn * 256 + bj * 128 + wc * 32 + 8 * fq;
;                     f32x4 v0 = acc[ai][bj][m][0] + *(const f32x4*)(xrow + col), v1 = acc[ai][bj][m][1] + *(const f32x4*)(xrow + col + 4);
;                     ss += (v0[0] * v0[0] + v0[1] * v0[1]) + (v0[2] * v0[2] + v0[3] * v0[3]) + (v1[0] * v1[0] + v1[1] * v1[1]) + (v1[2] * v1[2] + v1[3] * v1[3]);
;                     *(u32x4*)(X2B + (size_t)row * D + col) = pack8(v0, v1); }
;                 ss += __shfl_xor(ss, 16); ss += __shfl_xor(ss, 32);
;                 if (fq == 0) atomicAdd(rss + row, ss); }
.LBB0_793:
	s_waitcnt vmcnt(0)
	v_readlane_b32 s46, v254, 22
	s_barrier
	s_and_b32 s0, s44, 7
	s_lshr_b32 s1, s44, 3
	s_and_b32 s1, s1, 7
	s_lshl_b32 s0, s0, 3
	s_add_i32 s0, s0, s1
	s_mulk_i32 s0, 0x110
	s_addk_i32 s0, 0x100
	s_lshr_b32 s1, s44, 6
	v_readlane_b32 s2, v254, 21
	s_nop 3
	s_lshl_b32 s3, s1, 8
	s_mul_i32 s21, s2, 15360
	s_lshl_b32 s2, s2, 5
	s_add_i32 s3, s3, s2
	s_mov_b32 s4, 0x800
	s_add_u32 s8, s88, 0x3000000
	s_addc_u32 s9, s89, 0
	s_add_u32 s10, s88, 0x1a00000
	s_addc_u32 s11, s89, 0
	s_mov_b64 s[6:7], 0x2000
	s_mov_b64 s[12:13], 64
	v_and_b32_e32 v8, 15, v132
	v_lshrrev_b32_e32 v9, 4, v132
	v_add_u32_e32 v5, s0, v8
	v_lshl_add_u32 v2, v9, 3, s3
	v_lshlrev_b32_e32 v6, 4, v9
	v_lshrrev_b32_e32 v7, 3, v8
	v_lshlrev_b32_e32 v7, 5, v7
	v_xor_b32_e32 v6, v6, v7
	v_lshl_add_u32 v6, v8, 6, v6
	v_add_u32_e32 v6, s21, v6
	v_lshrrev_b32_e32 v36, 2, v132
	v_and_b32_e32 v37, 3, v132
	v_lshrrev_b32_e32 v38, 5, v132
	v_lshlrev_b32_e32 v37, 4, v37
	v_lshlrev_b32_e32 v38, 5, v38
	v_xor_b32_e32 v37, v37, v38
	v_add_u32_e32 v38, s0, v36
	v_lshrrev_b32_e32 v39, 2, v36
	v_and_b32_e32 v40, 3, v36
	v_lshl_add_u32 v39, v39, 3, v40
	v_add_u32_e32 v39, s3, v39
	v_mul_lo_u32 v10, v38, s4
	v_mul_lo_u32 v12, v39, s4
	v_mov_b32_e32 v11, 0
	v_mov_b32_e32 v13, 0
	v_add_u32_e32 v10, v10, v37
	v_add_u32_e32 v12, v12, v37
	v_lshl_add_u64 v[10:11], s[8:9], 0, v[10:11]
	v_lshl_add_u64 v[12:13], s[10:11], 0, v[12:13]
	v_lshl_add_u64 v[14:15], v[12:13], 0, s[6:7]
	s_cmp_lt_u32 s0, 0x4000
	s_cselect_b32 s22, s52, s54
	s_cselect_b32 s23, s53, s55
	s_cselect_b32 s20, 0, 0x4000
	v_subrev_u32_e32 v0, s20, v5
	v_lshlrev_b32_e32 v0, 12, v0
	v_lshl_add_u32 v0, v2, 2, v0
	v_mov_b32_e32 v1, 0
	v_lshl_add_u64 v[0:1], s[22:23], 0, v[0:1]
	global_load_dwordx4 v[120:123], v[0:1], off
	global_load_dwordx4 v[124:127], v[0:1], off offset:16
	v_mov_b32_e32 v16, v230
	v_mov_b32_e32 v17, v231
	v_mov_b32_e32 v18, v232
	v_mov_b32_e32 v19, v233
	v_mov_b32_e32 v20, v234
	v_mov_b32_e32 v21, v235
	v_mov_b32_e32 v22, v236
	v_mov_b32_e32 v23, v237
	s_waitcnt vmcnt(0)
	v_add_f32_e32 v16, v16, v120
	v_add_f32_e32 v17, v17, v121
	v_add_f32_e32 v18, v18, v122
	v_add_f32_e32 v19, v19, v123
	v_add_f32_e32 v20, v20, v124
	v_add_f32_e32 v21, v21, v125
	v_add_f32_e32 v22, v22, v126
	v_add_f32_e32 v23, v23, v127
	v_mul_f32_e32 v144, v16, v16
	v_fmac_f32_e32 v144, v17, v17
	v_fmac_f32_e32 v144, v18, v18
	v_fmac_f32_e32 v144, v19, v19
	v_fmac_f32_e32 v144, v20, v20
	v_fmac_f32_e32 v144, v21, v21
	v_fmac_f32_e32 v144, v22, v22
	v_fmac_f32_e32 v144, v23, v23
	v_cvt_pk_bf16_f32 v136, v16, v17
	v_cvt_pk_bf16_f32 v137, v18, v19
	v_cvt_pk_bf16_f32 v138, v20, v21
	v_cvt_pk_bf16_f32 v139, v22, v23
	s_add_u32 s22, s88, 0x18400000
	s_addc_u32 s23, s89, 0
	v_lshlrev_b32_e32 v0, 11, v5
	v_lshl_add_u32 v0, v2, 1, v0
	v_mov_b32_e32 v1, 0
	v_lshl_add_u64 v[0:1], s[22:23], 0, v[0:1]
	global_store_dwordx4 v[0:1], v[136:139], off
	v_lshlrev_b32_e32 v146, 2, v132
	v_xor_b32_e32 v145, 64, v146
	v_xor_b32_e32 v146, 0x80, v146
	ds_bpermute_b32 v147, v145, v144
	s_add_u32 s22, s88, 0x100000
	s_addc_u32 s23, s89, 0
	v_lshlrev_b32_e32 v0, 2, v5
	v_mov_b32_e32 v1, 0
	v_lshl_add_u64 v[0:1], s[22:23], 0, v[0:1]
	v_cmp_gt_u32_e32 vcc, 16, v132
	s_waitcnt lgkmcnt(0)
	v_add_f32_e32 v144, v144, v147
	ds_bpermute_b32 v147, v146, v144
	s_waitcnt lgkmcnt(0)
	v_add_f32_e32 v144, v144, v147
	s_and_saveexec_b64 s[22:23], vcc
	global_atomic_add_f32 v[0:1], v144, off
	s_or_b64 exec, exec, s[22:23]

; template <class Epi>
; __device__ __forceinline__ void gemm_phase(LAS unsigned char* lds, const Gemm g, const StaticOrder& S, const Epi& E) {
;     ...
;         const bool has_next = S.next(ui + 1, nxt);
;         const char* nA = has_next ? (const char*)g.A + (size_t)nxt.pm * tstep : cA; const char* nB = has_next ? (const char*)g.Bt + (size_t)nxt.pn * tstep : cB;
;         for (int t = 0; t < nt; t += 2) {
.LBB0_930:
	s_add_u32 s20, s20, 0xb0080
	s_addc_u32 s21, s21, 0
	s_add_u32 s49, s22, 0x100
	v_mov_b32_e32 v0, 0
	s_addc_u32 s50, s23, 0
	s_mov_b32 s51, -2
	s_waitcnt lgkmcnt(0)
	v_readlane_b32 s70, v254, 21
	s_nop 3
	s_lshr_b32 s68, s70, 2
	s_cmp_lt_u32 s70, 4
	s_cselect_b32 s71, 1, 0
	s_lshl_b32 s72, s70, 10
	s_add_i32 s72, s72, 0x20000
	s_mov_b32 s69, 0
	s_mov_b64 s[74:75], 0x100
	s_and_b32 s76, s44, 7
	s_lshr_b32 s77, s44, 3
	s_and_b32 s77, s77, 7
	s_lshl_b32 s76, s76, 3
	s_add_i32 s76, s76, s77
	s_mulk_i32 s76, 0x110
	s_addk_i32 s76, 0x100
	s_mov_b32 s77, 0x1600
	s_add_u32 s78, s88, 0xb800000
	s_addc_u32 s79, s89, 0
	s_lshl_b32 s73, s70, 6
	v_and_b32_e32 v246, 15, v132
	v_lshrrev_b32_e32 v247, 4, v132
	v_lshlrev_b32_e32 v247, 4, v247
	v_lshrrev_b32_e32 v248, 3, v246
	v_lshlrev_b32_e32 v248, 5, v248
	v_xor_b32_e32 v247, v247, v248
	v_lshl_add_u32 v242, v246, 6, v247
	v_add_u32_e32 v242, 0x20000, v242
	v_lshrrev_b32_e32 v246, 2, v132
	v_add_u32_e32 v246, s76, v246
	v_mul_lo_u32 v246, v246, s77
	v_and_b32_e32 v247, 3, v132
	v_lshlrev_b32_e32 v247, 4, v247
	v_lshrrev_b32_e32 v248, 5, v132
	v_lshlrev_b32_e32 v248, 5, v248
	v_xor_b32_e32 v247, v247, v248
	v_add3_u32 v244, v246, v247, s73
	v_mov_b32_e32 v245, 0
	v_lshl_add_u64 v[244:245], s[78:79], 0, v[244:245]
	v_mov_b32_e32 v226, 0
	v_mov_b32_e32 v227, 0
	v_mov_b32_e32 v228, 0
	v_mov_b32_e32 v229, 0
	v_mov_b32_e32 v230, 0
	v_mov_b32_e32 v231, 0
	v_mov_b32_e32 v232, 0
	v_mov_b32_e32 v233, 0
	s_cmp_eq_u32 s71, 0
	s_cbranch_scc1 .Lis_P6_i
	s_mov_b32 m0, s72
	s_nop 0
	global_load_lds_dwordx4 v[244:245], off
	v_lshl_add_u64 v[244:245], v[244:245], 0, s[74:75]

; #define PG8_STAGE(bufoff, gbase, voff) do { _Pragma("unroll") for (int _i = 0; _i < 2; ++_i) \
;         __builtin_amdgcn_global_load_lds((const unsigned*)((const char*)(gbase) + (voff)[_i]), (LAS unsigned*)(lds + (bufoff) + ldsw + _i * 8192), 16, 0, 0); } while (0)
; #define PG8_LDA(dst, b, h) do { _Pragma("unroll") for (int m = 0; m < 4; ++m) _Pragma("unroll") for (int k = 0; k < 2; ++k) dst[m][k] = *(const LAS bf16x8*)(lds + PG8_SA(b, h) + aoff + m * 2048 + k * 1024); } while (0)
; #define PG8_LDB(dst, b, h) do { _Pragma("unroll") for (int n = 0; n < 2; ++n) _Pragma("unroll") for (int k = 0; k < 2; ++k) dst[n][k] = *(const LAS bf16x8*)(lds + PG8_SB(b, h) + boff + n * 2048 + k * 1024); } while (0)
; #define PG8_MMA(ai, bj, At, Bt) do { __builtin_amdgcn_s_setprio(1); _Pragma("unroll") for (int m = 0; m < 4; ++m) _Pragma("unroll") for (int n = 0; n < 2; ++n) _Pragma("unroll") for (int k = 0; k < 2; ++k) \
;         acc[ai][bj][m][n] = __builtin_amdgcn_mfma_f32_16x16x32_bf16(Bt[n][k], At[m][k], acc[ai][bj][m][n], 0, 0, 0); __builtin_amdgcn_s_setprio(0); } while (0)
; #define PG8_WAIT_V(n) asm volatile("s_waitcnt vmcnt(" #n ")" ::: "memory")
; #define PG8_WAIT_L(n) asm volatile("s_waitcnt lgkmcnt(" #n ")" ::: "memory")
; #define PG8_BAR __builtin_amdgcn_s_barrier()
; #define PG8_SCHED __builtin_amdgcn_sched_barrier(0)
; template <class Epi>
; __device__ __forceinline__ void gemm_phase(LAS unsigned char* lds, const Gemm g, const StaticOrder& S, const Epi& E) {
;     ...
;             const char* a2 = last ? nA : cA + (size_t)(t + 2) * kstep; const char* b2 = last ? nB : cB + (size_t)(t + 2) * kstep;
;             const char* a3 = a2 + kstep; const char* b3 = b2 + kstep;
;             PG8_LDB(B0, 0, 0); PG8_LDB(B1, 0, 1); PG8_SCHED; PG8_LDA(At, 0, 0); PG8_STAGE(PG8_SA(1, 1), a1 + hstep, voffA);
;             PG8_WAIT_V(8); PG8_WAIT_L(0); PG8_BAR; PG8_MMA(0, 0, At, B0); PG8_MMA(0, 1, At, B1); PG8_BAR; PG8_SCHED;
;             PG8_LDA(At, 0, 1); PG8_STAGE(PG8_SB(0, 0), b2, voffB); PG8_STAGE(PG8_SB(0, 1), b2 + hstep, voffB); PG8_STAGE(PG8_SA(0, 0), a2, voffA);
.LBB0_931:
	ds_read_b128 v[146:149], v152
	ds_read_b128 v[156:159], v152 offset:1024
	ds_read_b128 v[160:163], v152 offset:2048
	ds_read_b128 v[164:167], v152 offset:3072
	ds_read_b128 v[168:171], v153
	ds_read_b128 v[172:175], v153 offset:1024
	ds_read_b128 v[176:179], v153 offset:2048
	ds_read_b128 v[180:183], v153 offset:3072
	s_add_u32 s22, s20, 0xfff50080
	s_addc_u32 s23, s21, -1
	s_cmp_eq_u32 s51, 40
	s_cselect_b32 s25, s1, s23
	s_cselect_b32 s24, s0, s22
	s_cselect_b32 s23, s19, s50
	s_cselect_b32 s22, s18, s49
	v_add_u32_e32 v243, s69, v242
	s_add_i32 s69, s69, 0x1000
	s_cmpk_eq_u32 s69, 0x3000
	s_cselect_b32 s69, 0, s69
	s_cmp_eq_u32 s71, 0
	s_cbranch_scc1 .Lis_P6_d
	s_add_i32 m0, s72, s69
	s_nop 0
	global_load_lds_dwordx4 v[244:245], off
	v_lshl_add_u64 v[244:245], v[244:245], 0, s[74:75]
.Lis_P6_d:
	v_lshl_add_u64 v[216:217], s[20:21], 0, v[134:135]
	s_add_i32 m0, s31, 0xc000
	ds_read_b128 v[184:187], v154
	ds_read_b128 v[188:191], v154 offset:1024
	ds_read_b128 v[192:195], v154 offset:2048
	ds_read_b128 v[196:199], v154 offset:3072
	ds_read_b128 v[200:203], v154 offset:4096
	ds_read_b128 v[204:207], v154 offset:5120
	ds_read_b128 v[208:211], v154 offset:6144
	ds_read_b128 v[212:215], v154 offset:7168
	global_load_lds_dwordx4 v[216:217], off
	v_lshl_add_u64 v[216:217], s[20:21], 0, v[140:141]
	s_add_i32 m0, s31, 0xe000
	s_nop 0
	global_load_lds_dwordx4 v[216:217], off
	s_waitcnt vmcnt(8)
	s_waitcnt lgkmcnt(0)
	s_barrier
	s_setprio 1
	s_waitcnt lgkmcnt(0)
	v_mfma_f32_16x16x32_bf16 v[124:127], v[146:149], v[184:187], v[124:127]
	v_mfma_f32_16x16x32_bf16 v[120:123], v[160:163], v[184:187], v[120:123]
	v_mfma_f32_16x16x32_bf16 v[108:111], v[146:149], v[192:195], v[108:111]
	v_mfma_f32_16x16x32_bf16 v[104:107], v[160:163], v[192:195], v[104:107]
	v_mfma_f32_16x16x32_bf16 v[92:95], v[146:149], v[200:203], v[92:95]
	v_mfma_f32_16x16x32_bf16 v[88:91], v[160:163], v[200:203], v[88:91]
	v_mfma_f32_16x16x32_bf16 v[76:79], v[146:149], v[208:211], v[76:79]
	v_mfma_f32_16x16x32_bf16 v[72:75], v[160:163], v[208:211], v[72:75]
	v_mfma_f32_16x16x32_bf16 v[124:127], v[156:159], v[188:191], v[124:127]
	v_mfma_f32_16x16x32_bf16 v[120:123], v[164:167], v[188:191], v[120:123]
	v_mfma_f32_16x16x32_bf16 v[108:111], v[156:159], v[196:199], v[108:111]
	v_mfma_f32_16x16x32_bf16 v[104:107], v[164:167], v[196:199], v[104:107]
	v_mfma_f32_16x16x32_bf16 v[92:95], v[156:159], v[204:207], v[92:95]
	v_mfma_f32_16x16x32_bf16 v[88:91], v[164:167], v[204:207], v[88:91]
	v_mfma_f32_16x16x32_bf16 v[76:79], v[156:159], v[212:215], v[76:79]
	v_mfma_f32_16x16x32_bf16 v[72:75], v[164:167], v[212:215], v[72:75]
	s_setprio 0
	s_setprio 1
	v_mfma_f32_16x16x32_bf16 v[116:119], v[168:171], v[184:187], v[116:119]
	v_mfma_f32_16x16x32_bf16 v[112:115], v[176:179], v[184:187], v[112:115]
	v_mfma_f32_16x16x32_bf16 v[100:103], v[168:171], v[192:195], v[100:103]
	v_mfma_f32_16x16x32_bf16 v[96:99], v[176:179], v[192:195], v[96:99]
	v_mfma_f32_16x16x32_bf16 v[84:87], v[168:171], v[200:203], v[84:87]
	v_mfma_f32_16x16x32_bf16 v[80:83], v[176:179], v[200:203], v[80:83]
	v_mfma_f32_16x16x32_bf16 v[68:71], v[168:171], v[208:211], v[68:71]
	v_mfma_f32_16x16x32_bf16 v[64:67], v[176:179], v[208:211], v[64:67]
	v_mfma_f32_16x16x32_bf16 v[116:119], v[172:175], v[188:191], v[116:119]
	v_mfma_f32_16x16x32_bf16 v[112:115], v[180:183], v[188:191], v[112:115]
	v_mfma_f32_16x16x32_bf16 v[100:103], v[172:175], v[196:199], v[100:103]
	v_mfma_f32_16x16x32_bf16 v[96:99], v[180:183], v[196:199], v[96:99]
	v_mfma_f32_16x16x32_bf16 v[84:87], v[172:175], v[204:207], v[84:87]
	v_mfma_f32_16x16x32_bf16 v[80:83], v[180:183], v[204:207], v[80:83]
	v_mfma_f32_16x16x32_bf16 v[68:71], v[172:175], v[212:215], v[68:71]
	v_mfma_f32_16x16x32_bf16 v[64:67], v[180:183], v[212:215], v[64:67]
	s_setprio 0
	s_barrier
	s_add_i32 s52, s42, s30
	v_lshl_add_u64 v[216:217], s[22:23], 0, v[130:131]
	s_mov_b32 m0, s52
	ds_read_b128 v[184:187], v154 offset:16384
	ds_read_b128 v[188:191], v154 offset:17408
	ds_read_b128 v[192:195], v154 offset:18432
	ds_read_b128 v[196:199], v154 offset:19456
	ds_read_b128 v[200:203], v154 offset:20480
	ds_read_b128 v[204:207], v154 offset:21504
	ds_read_b128 v[208:211], v154 offset:22528
	ds_read_b128 v[212:215], v154 offset:23552
	ds_read_b128 v[234:237], v243
	ds_read_b128 v[238:241], v243 offset:1024
	global_load_lds_dwordx4 v[216:217], off
	s_add_i32 m0, s52, 0x2000
	s_add_u32 s52, s22, 0xb0000
	v_lshl_add_u64 v[218:219], s[22:23], 0, v[138:139]
	s_addc_u32 s53, s23, 0
	s_add_i32 s54, s43, s30
	global_load_lds_dwordx4 v[218:219], off
	v_lshl_add_u64 v[220:221], s[52:53], 0, v[130:131]
	s_mov_b32 m0, s54
	v_lshl_add_u64 v[222:223], s[24:25], 0, v[136:137]
	global_load_lds_dwordx4 v[220:221], off
	v_lshl_add_u64 v[220:221], s[52:53], 0, v[138:139]
	s_add_i32 m0, s54, 0x2000
	s_nop 0
	global_load_lds_dwordx4 v[220:221], off
	v_lshl_add_u64 v[220:221], s[24:25], 0, v[128:129]
	s_mov_b32 m0, s31
	s_nop 0
	global_load_lds_dwordx4 v[220:221], off
	s_mov_b32 m0, s33
	s_nop 0
	global_load_lds_dwordx4 v[222:223], off
	s_waitcnt vmcnt(8)
	s_waitcnt lgkmcnt(0)
	s_barrier
; #define PG8_STAGE(bufoff, gbase, voff) do { _Pragma("unroll") for (int _i = 0; _i < 2; ++_i) \
;         __builtin_amdgcn_global_load_lds((const unsigned*)((const char*)(gbase) + (voff)[_i]), (LAS unsigned*)(lds + (bufoff) + ldsw + _i * 8192), 16, 0, 0); } while (0)
; #define PG8_LDA(dst, b, h) do { _Pragma("unroll") for (int m = 0; m < 4; ++m) _Pragma("unroll") for (int k = 0; k < 2; ++k) dst[m][k] = *(const LAS bf16x8*)(lds + PG8_SA(b, h) + aoff + m * 2048 + k * 1024); } while (0)
; #define PG8_LDB(dst, b, h) do { _Pragma("unroll") for (int n = 0; n < 2; ++n) _Pragma("unroll") for (int k = 0; k < 2; ++k) dst[n][k] = *(const LAS bf16x8*)(lds + PG8_SB(b, h) + boff + n * 2048 + k * 1024); } while (0)
; #define PG8_MMA(ai, bj, At, Bt) do { __builtin_amdgcn_s_setprio(1); _Pragma("unroll") for (int m = 0; m < 4; ++m) _Pragma("unroll") for (int n = 0; n < 2; ++n) _Pragma("unroll") for (int k = 0; k < 2; ++k) \
;         acc[ai][bj][m][n] = __builtin_amdgcn_mfma_f32_16x16x32_bf16(Bt[n][k], At[m][k], acc[ai][bj][m][n], 0, 0, 0); __builtin_amdgcn_s_setprio(0); } while (0)
; #define PG8_WAIT_V(n) asm volatile("s_waitcnt vmcnt(" #n ")" ::: "memory")
; #define PG8_WAIT_L(n) asm volatile("s_waitcnt lgkmcnt(" #n ")" ::: "memory")
; #define PG8_BAR __builtin_amdgcn_s_barrier()
; #define PG8_SCHED __builtin_amdgcn_sched_barrier(0)
; template <class Epi>
; __device__ __forceinline__ void gemm_phase(LAS unsigned char* lds, const Gemm g, const StaticOrder& S, const Epi& E) {
;     ...
;             PG8_WAIT_V(8); PG8_WAIT_L(0); PG8_BAR; PG8_MMA(1, 0, At, B0); PG8_MMA(1, 1, At, B1); PG8_BAR; PG8_SCHED;
;             PG8_LDB(B0, 1, 0); PG8_LDB(B1, 1, 1); PG8_SCHED; PG8_LDA(At, 1, 0); PG8_STAGE(PG8_SA(0, 1), a2 + hstep, voffA);
;             PG8_WAIT_V(8); PG8_WAIT_L(0); PG8_BAR; PG8_MMA(0, 0, At, B0); PG8_MMA(0, 1, At, B1); PG8_BAR; PG8_SCHED;
	s_setprio 1
	s_waitcnt lgkmcnt(0)
	v_mfma_f32_16x16x32_bf16 v[60:63], v[146:149], v[184:187], v[60:63]
	v_mfma_f32_16x16x32_bf16 v[56:59], v[160:163], v[184:187], v[56:59]
	v_mfma_f32_16x16x32_bf16 v[44:47], v[146:149], v[192:195], v[44:47]
	v_mfma_f32_16x16x32_bf16 v[40:43], v[160:163], v[192:195], v[40:43]
	v_mfma_f32_16x16x32_bf16 v[28:31], v[146:149], v[200:203], v[28:31]
	v_mfma_f32_16x16x32_bf16 v[24:27], v[160:163], v[200:203], v[24:27]
	v_mfma_f32_16x16x32_bf16 v[12:15], v[146:149], v[208:211], v[12:15]
	v_mfma_f32_16x16x32_bf16 v[8:11], v[160:163], v[208:211], v[8:11]
	v_mfma_f32_16x16x32_bf16 v[60:63], v[156:159], v[188:191], v[60:63]
	v_mfma_f32_16x16x32_bf16 v[56:59], v[164:167], v[188:191], v[56:59]
	v_mfma_f32_16x16x32_bf16 v[44:47], v[156:159], v[196:199], v[44:47]
	v_mfma_f32_16x16x32_bf16 v[40:43], v[164:167], v[196:199], v[40:43]
	v_mfma_f32_16x16x32_bf16 v[28:31], v[156:159], v[204:207], v[28:31]
	v_mfma_f32_16x16x32_bf16 v[24:27], v[164:167], v[204:207], v[24:27]
	v_mfma_f32_16x16x32_bf16 v[12:15], v[156:159], v[212:215], v[12:15]
	v_mfma_f32_16x16x32_bf16 v[8:11], v[164:167], v[212:215], v[8:11]
	s_setprio 0
	s_setprio 1
	v_mfma_f32_16x16x32_bf16 v[52:55], v[168:171], v[184:187], v[52:55]
	v_mfma_f32_16x16x32_bf16 v[48:51], v[176:179], v[184:187], v[48:51]
	v_mfma_f32_16x16x32_bf16 v[36:39], v[168:171], v[192:195], v[36:39]
	v_mfma_f32_16x16x32_bf16 v[32:35], v[176:179], v[192:195], v[32:35]
	v_mfma_f32_16x16x32_bf16 v[20:23], v[168:171], v[200:203], v[20:23]
	v_mfma_f32_16x16x32_bf16 v[16:19], v[176:179], v[200:203], v[16:19]
	v_mfma_f32_16x16x32_bf16 v[4:7], v[168:171], v[208:211], v[4:7]
	v_mfma_f32_16x16x32_bf16 v[0:3], v[176:179], v[208:211], v[0:3]
	v_mfma_f32_16x16x32_bf16 v[52:55], v[172:175], v[188:191], v[52:55]
	v_mfma_f32_16x16x32_bf16 v[48:51], v[180:183], v[188:191], v[48:51]
	v_mfma_f32_16x16x32_bf16 v[36:39], v[172:175], v[196:199], v[36:39]
	v_mfma_f32_16x16x32_bf16 v[32:35], v[180:183], v[196:199], v[32:35]
	v_mfma_f32_16x16x32_bf16 v[20:23], v[172:175], v[204:207], v[20:23]
	v_mfma_f32_16x16x32_bf16 v[16:19], v[180:183], v[204:207], v[16:19]
	v_mfma_f32_16x16x32_bf16 v[4:7], v[172:175], v[212:215], v[4:7]
	v_mfma_f32_16x16x32_bf16 v[0:3], v[180:183], v[212:215], v[0:3]
	s_cmp_eq_u32 s68, 0
	s_cbranch_scc1 .Lis_P6_b0
	v_mfma_f32_16x16x32_bf16 v[226:229], v[168:171], v[234:237], v[226:229]
	v_mfma_f32_16x16x32_bf16 v[230:233], v[176:179], v[234:237], v[230:233]
	v_mfma_f32_16x16x32_bf16 v[226:229], v[172:175], v[238:241], v[226:229]
	v_mfma_f32_16x16x32_bf16 v[230:233], v[180:183], v[238:241], v[230:233]
	s_branch .Lis_P6_bj
.Lis_P6_b0:
	v_mfma_f32_16x16x32_bf16 v[226:229], v[146:149], v[234:237], v[226:229]
	v_mfma_f32_16x16x32_bf16 v[230:233], v[160:163], v[234:237], v[230:233]
	v_mfma_f32_16x16x32_bf16 v[226:229], v[156:159], v[238:241], v[226:229]
	v_mfma_f32_16x16x32_bf16 v[230:233], v[164:167], v[238:241], v[230:233]
.Lis_P6_bj:
	s_setprio 0
	s_barrier
	s_add_i32 s52, 0, 0x18000
	s_add_i32 s53, 0, 0x1c000
	v_add_u32_e32 v164, s52, v150
	v_add_u32_e32 v180, s53, v150
	ds_read_b128 v[146:149], v164
	ds_read_b128 v[156:159], v164 offset:1024
	ds_read_b128 v[160:163], v164 offset:2048
	ds_read_b128 v[164:167], v164 offset:3072
	ds_read_b128 v[168:171], v180
	ds_read_b128 v[172:175], v180 offset:1024
	ds_read_b128 v[176:179], v180 offset:2048
	ds_read_b128 v[180:183], v180 offset:3072
	s_add_u32 s24, s24, 0xb0000
	s_addc_u32 s25, s25, 0
	s_mov_b32 m0, s34
	v_lshl_add_u64 v[224:225], s[24:25], 0, v[128:129]
	ds_read_b128 v[184:187], v154 offset:32768
	ds_read_b128 v[188:191], v154 offset:33792
	ds_read_b128 v[192:195], v154 offset:34816
	ds_read_b128 v[196:199], v154 offset:35840
	ds_read_b128 v[200:203], v154 offset:36864
	ds_read_b128 v[204:207], v154 offset:37888
	ds_read_b128 v[208:211], v154 offset:38912
	ds_read_b128 v[212:215], v154 offset:39936
	global_load_lds_dwordx4 v[224:225], off
	v_lshl_add_u64 v[224:225], s[24:25], 0, v[136:137]
	s_mov_b32 m0, s35
	s_nop 0
	global_load_lds_dwordx4 v[224:225], off
	s_waitcnt vmcnt(8)
	s_waitcnt lgkmcnt(0)
	s_barrier
; #define PG8_STAGE(bufoff, gbase, voff) do { _Pragma("unroll") for (int _i = 0; _i < 2; ++_i) \
;         __builtin_amdgcn_global_load_lds((const unsigned*)((const char*)(gbase) + (voff)[_i]), (LAS unsigned*)(lds + (bufoff) + ldsw + _i * 8192), 16, 0, 0); } while (0)
; #define PG8_LDA(dst, b, h) do { _Pragma("unroll") for (int m = 0; m < 4; ++m) _Pragma("unroll") for (int k = 0; k < 2; ++k) dst[m][k] = *(const LAS bf16x8*)(lds + PG8_SA(b, h) + aoff + m * 2048 + k * 1024); } while (0)
; #define PG8_MMA(ai, bj, At, Bt) do { __builtin_amdgcn_s_setprio(1); _Pragma("unroll") for (int m = 0; m < 4; ++m) _Pragma("unroll") for (int n = 0; n < 2; ++n) _Pragma("unroll") for (int k = 0; k < 2; ++k) \
;         acc[ai][bj][m][n] = __builtin_amdgcn_mfma_f32_16x16x32_bf16(Bt[n][k], At[m][k], acc[ai][bj][m][n], 0, 0, 0); __builtin_amdgcn_s_setprio(0); } while (0)
; #define PG8_WAIT_V(n) asm volatile("s_waitcnt vmcnt(" #n ")" ::: "memory")
; #define PG8_WAIT_L(n) asm volatile("s_waitcnt lgkmcnt(" #n ")" ::: "memory")
; #define PG8_BAR __builtin_amdgcn_s_barrier()
; #define PG8_SCHED __builtin_amdgcn_sched_barrier(0)
; template <class Epi>
; __device__ __forceinline__ void gemm_phase(LAS unsigned char* lds, const Gemm g, const StaticOrder& S, const Epi& E) {
;     ...
;             PG8_WAIT_V(8); PG8_WAIT_L(0); PG8_BAR; PG8_MMA(0, 0, At, B0); PG8_MMA(0, 1, At, B1); PG8_BAR; PG8_SCHED;
;             PG8_LDA(At, 1, 1); PG8_STAGE(PG8_SB(1, 0), b3, voffB); PG8_STAGE(PG8_SB(1, 1), b3 + hstep, voffB); PG8_STAGE(PG8_SA(1, 0), a3, voffA);
;             PG8_WAIT_V(8); PG8_WAIT_L(0); PG8_BAR; PG8_MMA(1, 0, At, B0); PG8_MMA(1, 1, At, B1); PG8_BAR; PG8_SCHED;
	s_setprio 1
	s_waitcnt lgkmcnt(0)
	v_mfma_f32_16x16x32_bf16 v[124:127], v[146:149], v[184:187], v[124:127]
	v_mfma_f32_16x16x32_bf16 v[120:123], v[160:163], v[184:187], v[120:123]
	v_mfma_f32_16x16x32_bf16 v[108:111], v[146:149], v[192:195], v[108:111]
	v_mfma_f32_16x16x32_bf16 v[104:107], v[160:163], v[192:195], v[104:107]
	v_mfma_f32_16x16x32_bf16 v[92:95], v[146:149], v[200:203], v[92:95]
	v_mfma_f32_16x16x32_bf16 v[88:91], v[160:163], v[200:203], v[88:91]
	v_mfma_f32_16x16x32_bf16 v[76:79], v[146:149], v[208:211], v[76:79]
	v_mfma_f32_16x16x32_bf16 v[72:75], v[160:163], v[208:211], v[72:75]
	v_mfma_f32_16x16x32_bf16 v[124:127], v[156:159], v[188:191], v[124:127]
	v_mfma_f32_16x16x32_bf16 v[120:123], v[164:167], v[188:191], v[120:123]
	v_mfma_f32_16x16x32_bf16 v[108:111], v[156:159], v[196:199], v[108:111]
	v_mfma_f32_16x16x32_bf16 v[104:107], v[164:167], v[196:199], v[104:107]
	v_mfma_f32_16x16x32_bf16 v[92:95], v[156:159], v[204:207], v[92:95]
	v_mfma_f32_16x16x32_bf16 v[88:91], v[164:167], v[204:207], v[88:91]
	v_mfma_f32_16x16x32_bf16 v[76:79], v[156:159], v[212:215], v[76:79]
	v_mfma_f32_16x16x32_bf16 v[72:75], v[164:167], v[212:215], v[72:75]
	s_setprio 0
	s_setprio 1
	v_mfma_f32_16x16x32_bf16 v[116:119], v[168:171], v[184:187], v[116:119]
	v_mfma_f32_16x16x32_bf16 v[112:115], v[176:179], v[184:187], v[112:115]
	v_mfma_f32_16x16x32_bf16 v[100:103], v[168:171], v[192:195], v[100:103]
	v_mfma_f32_16x16x32_bf16 v[96:99], v[176:179], v[192:195], v[96:99]
	v_mfma_f32_16x16x32_bf16 v[84:87], v[168:171], v[200:203], v[84:87]
	v_mfma_f32_16x16x32_bf16 v[80:83], v[176:179], v[200:203], v[80:83]
	v_mfma_f32_16x16x32_bf16 v[68:71], v[168:171], v[208:211], v[68:71]
	v_mfma_f32_16x16x32_bf16 v[64:67], v[176:179], v[208:211], v[64:67]
	v_mfma_f32_16x16x32_bf16 v[116:119], v[172:175], v[188:191], v[116:119]
	v_mfma_f32_16x16x32_bf16 v[112:115], v[180:183], v[188:191], v[112:115]
	v_mfma_f32_16x16x32_bf16 v[100:103], v[172:175], v[196:199], v[100:103]
	v_mfma_f32_16x16x32_bf16 v[96:99], v[180:183], v[196:199], v[96:99]
	v_mfma_f32_16x16x32_bf16 v[84:87], v[172:175], v[204:207], v[84:87]
	v_mfma_f32_16x16x32_bf16 v[80:83], v[180:183], v[204:207], v[80:83]
	v_mfma_f32_16x16x32_bf16 v[68:71], v[172:175], v[212:215], v[68:71]
	v_mfma_f32_16x16x32_bf16 v[64:67], v[180:183], v[212:215], v[64:67]
	s_setprio 0
	s_barrier
	s_add_i32 s24, s52, s30
	v_lshl_add_u64 v[216:217], v[216:217], 0, s[14:15]
	s_mov_b32 m0, s24
	ds_read_b128 v[184:187], v154 offset:49152
	ds_read_b128 v[188:191], v154 offset:50176
	ds_read_b128 v[192:195], v154 offset:51200
	ds_read_b128 v[196:199], v154 offset:52224
	ds_read_b128 v[200:203], v154 offset:53248
	ds_read_b128 v[204:207], v154 offset:54272
	ds_read_b128 v[208:211], v154 offset:55296
	ds_read_b128 v[212:215], v154 offset:56320
	ds_read_b128 v[234:237], v243 offset:2048
	ds_read_b128 v[238:241], v243 offset:3072
	global_load_lds_dwordx4 v[216:217], off
	s_add_i32 m0, s24, 0x2000
	s_add_u32 s22, s22, 0xb0080
	v_lshl_add_u64 v[216:217], v[218:219], 0, s[14:15]
	s_addc_u32 s23, s23, 0
	s_add_i32 s24, s53, s30
	global_load_lds_dwordx4 v[216:217], off
	v_lshl_add_u64 v[216:217], s[22:23], 0, v[130:131]
	s_mov_b32 m0, s24
	s_nop 0
	global_load_lds_dwordx4 v[216:217], off
	v_lshl_add_u64 v[216:217], s[22:23], 0, v[138:139]
	s_add_i32 m0, s24, 0x2000
	s_nop 0
	global_load_lds_dwordx4 v[216:217], off
	v_lshl_add_u64 v[216:217], v[220:221], 0, s[14:15]
	s_mov_b32 m0, s37
	s_nop 0
	global_load_lds_dwordx4 v[216:217], off
	v_lshl_add_u64 v[216:217], v[222:223], 0, s[14:15]
	s_mov_b32 m0, s38
	s_nop 0
	global_load_lds_dwordx4 v[216:217], off
	s_waitcnt vmcnt(8)
	s_waitcnt lgkmcnt(0)
	s_barrier
	s_setprio 1
	s_waitcnt lgkmcnt(0)
	v_mfma_f32_16x16x32_bf16 v[60:63], v[146:149], v[184:187], v[60:63]
	v_mfma_f32_16x16x32_bf16 v[56:59], v[160:163], v[184:187], v[56:59]
	v_mfma_f32_16x16x32_bf16 v[44:47], v[146:149], v[192:195], v[44:47]
	v_mfma_f32_16x16x32_bf16 v[40:43], v[160:163], v[192:195], v[40:43]
	v_mfma_f32_16x16x32_bf16 v[28:31], v[146:149], v[200:203], v[28:31]
	v_mfma_f32_16x16x32_bf16 v[24:27], v[160:163], v[200:203], v[24:27]
	v_mfma_f32_16x16x32_bf16 v[12:15], v[146:149], v[208:211], v[12:15]
	v_mfma_f32_16x16x32_bf16 v[8:11], v[160:163], v[208:211], v[8:11]
	v_mfma_f32_16x16x32_bf16 v[60:63], v[156:159], v[188:191], v[60:63]
	v_mfma_f32_16x16x32_bf16 v[56:59], v[164:167], v[188:191], v[56:59]
	v_mfma_f32_16x16x32_bf16 v[44:47], v[156:159], v[196:199], v[44:47]
	v_mfma_f32_16x16x32_bf16 v[40:43], v[164:167], v[196:199], v[40:43]
	v_mfma_f32_16x16x32_bf16 v[28:31], v[156:159], v[204:207], v[28:31]
	v_mfma_f32_16x16x32_bf16 v[24:27], v[164:167], v[204:207], v[24:27]
	v_mfma_f32_16x16x32_bf16 v[12:15], v[156:159], v[212:215], v[12:15]
	v_mfma_f32_16x16x32_bf16 v[8:11], v[164:167], v[212:215], v[8:11]
	s_setprio 0
	s_setprio 1
	v_mfma_f32_16x16x32_bf16 v[52:55], v[168:171], v[184:187], v[52:55]
	v_mfma_f32_16x16x32_bf16 v[48:51], v[176:179], v[184:187], v[48:51]
	v_mfma_f32_16x16x32_bf16 v[36:39], v[168:171], v[192:195], v[36:39]
	v_mfma_f32_16x16x32_bf16 v[32:35], v[176:179], v[192:195], v[32:35]
	v_mfma_f32_16x16x32_bf16 v[20:23], v[168:171], v[200:203], v[20:23]
	v_mfma_f32_16x16x32_bf16 v[16:19], v[176:179], v[200:203], v[16:19]
	v_mfma_f32_16x16x32_bf16 v[4:7], v[168:171], v[208:211], v[4:7]
	v_mfma_f32_16x16x32_bf16 v[0:3], v[176:179], v[208:211], v[0:3]
	v_mfma_f32_16x16x32_bf16 v[52:55], v[172:175], v[188:191], v[52:55]
	v_mfma_f32_16x16x32_bf16 v[48:51], v[180:183], v[188:191], v[48:51]
	v_mfma_f32_16x16x32_bf16 v[36:39], v[172:175], v[196:199], v[36:39]
	v_mfma_f32_16x16x32_bf16 v[32:35], v[180:183], v[196:199], v[32:35]
	v_mfma_f32_16x16x32_bf16 v[20:23], v[172:175], v[204:207], v[20:23]
	v_mfma_f32_16x16x32_bf16 v[16:19], v[180:183], v[204:207], v[16:19]
	v_mfma_f32_16x16x32_bf16 v[4:7], v[172:175], v[212:215], v[4:7]
	v_mfma_f32_16x16x32_bf16 v[0:3], v[180:183], v[212:215], v[0:3]
	s_cmp_eq_u32 s68, 0
	s_cbranch_scc1 .Lis_P6_d0
	v_mfma_f32_16x16x32_bf16 v[226:229], v[168:171], v[234:237], v[226:229]
	v_mfma_f32_16x16x32_bf16 v[230:233], v[176:179], v[234:237], v[230:233]
	v_mfma_f32_16x16x32_bf16 v[226:229], v[172:175], v[238:241], v[226:229]
	v_mfma_f32_16x16x32_bf16 v[230:233], v[180:183], v[238:241], v[230:233]
	s_branch .Lis_P6_dj

; #define PG8_MMA(ai, bj, At, Bt) do { __builtin_amdgcn_s_setprio(1); _Pragma("unroll") for (int m = 0; m < 4; ++m) _Pragma("unroll") for (int n = 0; n < 2; ++n) _Pragma("unroll") for (int k = 0; k < 2; ++k) \
;         acc[ai][bj][m][n] = __builtin_amdgcn_mfma_f32_16x16x32_bf16(Bt[n][k], At[m][k], acc[ai][bj][m][n], 0, 0, 0); __builtin_amdgcn_s_setprio(0); } while (0)
; #define PG8_WAIT_V(n) asm volatile("s_waitcnt vmcnt(" #n ")" ::: "memory")
; #define PG8_WAIT_L(n) asm volatile("s_waitcnt lgkmcnt(" #n ")" ::: "memory")
; #define PG8_BAR __builtin_amdgcn_s_barrier()
; #define PG8_SCHED __builtin_amdgcn_sched_barrier(0)
; template <class Epi>
; __device__ __forceinline__ void gemm_phase(LAS unsigned char* lds, const Gemm g, const StaticOrder& S, const Epi& E) {
;     ...
;             PG8_WAIT_V(8); PG8_WAIT_L(0); PG8_BAR; PG8_MMA(1, 0, At, B0); PG8_MMA(1, 1, At, B1); PG8_BAR; PG8_SCHED;
;         }
;         if (wr == 0) PG8_BAR;
.Lis_P6_dj:
	s_setprio 0
	s_barrier
	s_add_i32 s51, s51, 2
	s_add_u32 s20, s20, 0x100
	s_addc_u32 s21, s21, 0
	s_add_u32 s49, s49, 0x100
	s_addc_u32 s50, s50, 0
	s_cmp_gt_u32 s51, 41
	s_cbranch_scc0 .LBB0_931
	s_and_b64 vcc, exec, s[16:17]
	s_cbranch_vccz .LBB0_934
	s_barrier

; __device__ __forceinline__ u32x4 pack8(f32x4 a, f32x4 b) { u32x4 w; w.x = cvt_pk_bf16(a[0], a[1]); w.y = cvt_pk_bf16(a[2], a[3]); w.z = cvt_pk_bf16(b[0], b[1]); w.w = cvt_pk_bf16(b[2], b[3]); return w; }
;     __device__ __forceinline__ void operator()(const f32x4 (&acc)[2][2][4][2], const pg8::Unit& u, int wr, int wc, int fr, int fq) const {
;     ...
;             for (int m = 0; m < 4; ++m) { const int row = u.pm * 256 + ai * 128 + wr * 64 + m * 16 + fr; float ss = 0.f;
; #pragma unroll
;                 for (int bj = 0; bj < 2; ++bj) { const int col = u.pn * 256 + bj * 128 + wc * 32 + 8 * fq;
;                     f32x4 x0, x1; unpack_bf16x8(*(const u32x4*)(X2B + (size_t)row * D + col), x0, x1);
;                     const f32x4 v0 = acc[ai][bj][m][0] + x0, v1 = acc[ai][bj][m][1] + x1;
;                     ss += (v0[0] * v0[0] + v0[1] * v0[1]) + (v0[2] * v0[2] + v0[3] * v0[3]) + (v1[0] * v1[0] + v1[1] * v1[1]) + (v1[2] * v1[2] + v1[3] * v1[3]);
;                     *(u32x4*)(X3B + (size_t)row * D + col) = pack8(v0, v1); }
;                 ss += __shfl_xor(ss, 16); ss += __shfl_xor(ss, 32);
;                 if (fq == 0) atomicAdd(rss + row, ss); }
.LBB0_953:
	s_waitcnt vmcnt(0)
	v_readlane_b32 s46, v254, 22
	s_barrier
	s_and_b32 s0, s44, 7
	s_lshr_b32 s1, s44, 3
	s_and_b32 s1, s1, 7
	s_lshl_b32 s0, s0, 3
	s_add_i32 s0, s0, s1
	s_mulk_i32 s0, 0x110
	s_addk_i32 s0, 0x100
	s_lshr_b32 s1, s44, 6
	v_readlane_b32 s2, v254, 21
	s_nop 3
	s_lshl_b32 s3, s1, 8
	s_mul_i32 s21, s2, 15360
	s_lshl_b32 s2, s2, 5
	s_add_i32 s3, s3, s2
	s_mov_b32 s4, 0x1600
	s_add_u32 s8, s88, 0xb800000
	s_addc_u32 s9, s89, 0
	s_add_u32 s10, s88, 0x2700000
	s_addc_u32 s11, s89, 0
	s_mov_b64 s[6:7], 0x5800
	s_mov_b64 s[12:13], 64
	v_and_b32_e32 v8, 15, v132
	v_lshrrev_b32_e32 v9, 4, v132
	v_add_u32_e32 v5, s0, v8
	v_lshl_add_u32 v2, v9, 3, s3
	v_lshlrev_b32_e32 v6, 4, v9
	v_lshrrev_b32_e32 v7, 3, v8
	v_lshlrev_b32_e32 v7, 5, v7
	v_xor_b32_e32 v6, v6, v7
	v_lshl_add_u32 v6, v8, 6, v6
	v_add_u32_e32 v6, s21, v6
	v_lshrrev_b32_e32 v36, 2, v132
	v_and_b32_e32 v37, 3, v132
	v_lshrrev_b32_e32 v38, 5, v132
	v_lshlrev_b32_e32 v37, 4, v37
	v_lshlrev_b32_e32 v38, 5, v38
	v_xor_b32_e32 v37, v37, v38
	v_add_u32_e32 v38, s0, v36
	v_lshrrev_b32_e32 v39, 2, v36
	v_and_b32_e32 v40, 3, v36
	v_lshl_add_u32 v39, v39, 3, v40
	v_add_u32_e32 v39, s3, v39
	v_mul_lo_u32 v10, v38, s4
	v_mul_lo_u32 v12, v39, s4
	v_mov_b32_e32 v11, 0
	v_mov_b32_e32 v13, 0
	v_add_u32_e32 v10, v10, v37
	v_add_u32_e32 v12, v12, v37
	v_lshl_add_u64 v[10:11], s[8:9], 0, v[10:11]
	v_lshl_add_u64 v[12:13], s[10:11], 0, v[12:13]
	v_lshl_add_u64 v[14:15], v[12:13], 0, s[6:7]
	s_add_u32 s22, s88, 0x18400000
	s_addc_u32 s23, s89, 0
	v_lshlrev_b32_e32 v0, 11, v5
	v_lshl_add_u32 v0, v2, 1, v0
	v_mov_b32_e32 v1, 0
	v_lshl_add_u64 v[0:1], s[22:23], 0, v[0:1]
	global_load_dwordx4 v[120:123], v[0:1], off
	v_mov_b32_e32 v16, v226
	v_mov_b32_e32 v17, v227
	v_mov_b32_e32 v18, v228
	v_mov_b32_e32 v19, v229
	v_mov_b32_e32 v20, v230
	v_mov_b32_e32 v21, v231
	v_mov_b32_e32 v22, v232
	v_mov_b32_e32 v23, v233
	s_waitcnt vmcnt(0)
	v_lshlrev_b32_e32 v136, 16, v120
	v_and_b32_e32 v137, 0xffff0000, v120
	v_lshlrev_b32_e32 v138, 16, v121
	v_and_b32_e32 v139, 0xffff0000, v121
	v_lshlrev_b32_e32 v140, 16, v122
	v_and_b32_e32 v141, 0xffff0000, v122
	v_lshlrev_b32_e32 v142, 16, v123
	v_and_b32_e32 v143, 0xffff0000, v123
	v_add_f32_e32 v16, v16, v136
	v_add_f32_e32 v17, v17, v137
	v_add_f32_e32 v18, v18, v138
	v_add_f32_e32 v19, v19, v139
	v_add_f32_e32 v20, v20, v140
	v_add_f32_e32 v21, v21, v141
	v_add_f32_e32 v22, v22, v142
	v_add_f32_e32 v23, v23, v143
	v_mul_f32_e32 v144, v16, v16
	v_fmac_f32_e32 v144, v17, v17
	v_fmac_f32_e32 v144, v18, v18
	v_fmac_f32_e32 v144, v19, v19
	v_fmac_f32_e32 v144, v20, v20
	v_fmac_f32_e32 v144, v21, v21
	v_fmac_f32_e32 v144, v22, v22
	v_fmac_f32_e32 v144, v23, v23
	v_cvt_pk_bf16_f32 v136, v16, v17
	v_cvt_pk_bf16_f32 v137, v18, v19
	v_cvt_pk_bf16_f32 v138, v20, v21
	v_cvt_pk_bf16_f32 v139, v22, v23
	s_add_u32 s22, s88, 0x9600000
	s_addc_u32 s23, s89, 0
	v_lshlrev_b32_e32 v0, 11, v5
	v_lshl_add_u32 v0, v2, 1, v0
	v_mov_b32_e32 v1, 0
	v_lshl_add_u64 v[0:1], s[22:23], 0, v[0:1]
	global_store_dwordx4 v[0:1], v[136:139], off
	v_lshlrev_b32_e32 v146, 2, v132
	v_xor_b32_e32 v145, 64, v146
	v_xor_b32_e32 v146, 0x80, v146
	ds_bpermute_b32 v147, v145, v144
	s_add_u32 s22, s88, 0x120000
	s_addc_u32 s23, s89, 0
	v_lshlrev_b32_e32 v0, 2, v5
	v_mov_b32_e32 v1, 0
	v_lshl_add_u64 v[0:1], s[22:23], 0, v[0:1]
	v_cmp_gt_u32_e32 vcc, 16, v132
	s_waitcnt lgkmcnt(0)
	v_add_f32_e32 v144, v144, v147
	ds_bpermute_b32 v147, v146, v144
	s_waitcnt lgkmcnt(0)
	v_add_f32_e32 v144, v144, v147
	s_and_saveexec_b64 s[22:23], vcc
	global_atomic_add_f32 v[0:1], v144, off
	s_or_b64 exec, exec, s[22:23]
